# P1 rmsnorm+modulate: all modulation loads hoisted to trip start, ladder without memory waits
# speedup vs baseline: 1.1063x; 1.0083x over previous
.LBB0_167:
	s_or_b64 exec, exec, s[14:15]
	v_lshl_add_u64 v[4:5], v[4:5], 0, v[18:19]
	global_load_dwordx4 v[48:51], v[4:5], off
	global_load_dwordx4 v[52:55], v[4:5], off offset:1024
	global_load_dwordx4 v[56:59], v[4:5], off offset:2048
	global_load_dwordx4 v[60:63], v[4:5], off offset:3072
	v_lshl_add_u64 v[2:3], v[2:3], 0, v[18:19]
	global_load_dwordx4 v[14:17], v[2:3], off
	global_load_dwordx4 v[10:13], v[2:3], off offset:1024
	global_load_dwordx4 v[6:9], v[2:3], off offset:2048
	s_nop 0
	global_load_dwordx4 v[2:5], v[2:3], off offset:3072
	v_lshl_add_u64 v[40:41], v[40:41], 2, s[40:41]
	v_mov_b32_e32 v27, v19
	v_lshl_add_u64 v[72:73], v[40:41], 0, s[10:11]
	v_lshl_add_u64 v[40:41], v[40:41], 0, v[26:27]
	v_lshl_add_u64 v[68:69], v[72:73], 0, v[26:27]
	global_load_dwordx4 v[64:67], v[40:41], off
	s_nop 0
	global_load_dwordx4 v[68:71], v[68:69], off
	v_lshl_add_u64 v[142:143], v[72:73], 0, v[26:27]
	global_load_dwordx4 v[144:147], v[40:41], off offset:1024
	global_load_dwordx4 v[148:151], v[40:41], off offset:2048
	global_load_dwordx4 v[152:155], v[40:41], off offset:3072
	global_load_dwordx4 v[156:159], v[142:143], off offset:1024
	global_load_dwordx4 v[160:163], v[142:143], off offset:2048
	global_load_dwordx4 v[164:167], v[142:143], off offset:3072
	v_lshl_add_u64 v[168:169], v[38:39], 2, s[40:41]
	v_lshl_add_u64 v[168:169], v[168:169], 0, v[26:27]
	v_lshl_add_u64 v[170:171], v[168:169], 0, s[10:11]
	global_load_dwordx4 v[172:175], v[168:169], off
	global_load_dwordx4 v[176:179], v[168:169], off offset:1024
	global_load_dwordx4 v[180:183], v[168:169], off offset:2048
	global_load_dwordx4 v[184:187], v[168:169], off offset:3072
	global_load_dwordx4 v[188:191], v[170:171], off
	global_load_dwordx4 v[192:195], v[170:171], off offset:1024
	global_load_dwordx4 v[196:199], v[170:171], off offset:2048
	global_load_dwordx4 v[200:203], v[170:171], off offset:3072
	v_mov_b32_e32 v29, v19
	v_lshlrev_b64 v[36:37], 11, v[36:37]
	v_lshl_add_u64 v[22:23], v[22:23], 0, s[4:5]
	s_waitcnt vmcnt(23)
	v_mov_b32_e32 v80, v49
	s_waitcnt vmcnt(22)
	v_mov_b32_e32 v81, v53
	s_waitcnt vmcnt(21)
	v_mov_b32_e32 v88, v57
	s_waitcnt vmcnt(20)
	v_mov_b32_e32 v89, v61
	s_waitcnt vmcnt(19)
	v_mov_b32_e32 v96, v15
	s_waitcnt vmcnt(18)
	v_mov_b32_e32 v97, v11
	v_mov_b32_e32 v78, v48
	v_mov_b32_e32 v79, v52
	v_mov_b32_e32 v86, v56
	v_mov_b32_e32 v87, v60
	v_mov_b32_e32 v94, v14
	v_mov_b32_e32 v95, v10
	s_waitcnt vmcnt(17)
	v_mov_b32_e32 v104, v7
	s_waitcnt vmcnt(16)
	v_mov_b32_e32 v105, v3
	v_pk_mul_f32 v[80:81], v[80:81], v[80:81]
	v_pk_mul_f32 v[88:89], v[88:89], v[88:89]
	v_pk_mul_f32 v[96:97], v[96:97], v[96:97]
	v_mov_b32_e32 v74, v50
	v_mov_b32_e32 v75, v54
	v_mov_b32_e32 v82, v58
	v_mov_b32_e32 v83, v62
	v_mov_b32_e32 v90, v16
	v_mov_b32_e32 v91, v12
	v_mov_b32_e32 v102, v6
	v_mov_b32_e32 v103, v2
	v_pk_mul_f32 v[104:105], v[104:105], v[104:105]
	v_pk_fma_f32 v[78:79], v[78:79], v[78:79], v[80:81]
	v_pk_fma_f32 v[80:81], v[86:87], v[86:87], v[88:89]
	v_pk_fma_f32 v[86:87], v[94:95], v[94:95], v[96:97]
	v_mov_b32_e32 v76, v51
	v_mov_b32_e32 v77, v55
	v_mov_b32_e32 v84, v59
	v_mov_b32_e32 v85, v63
	v_mov_b32_e32 v92, v17
	v_mov_b32_e32 v93, v13
	v_mov_b32_e32 v98, v8
	v_mov_b32_e32 v99, v4
	v_pk_fma_f32 v[88:89], v[102:103], v[102:103], v[104:105]
	v_pk_fma_f32 v[74:75], v[74:75], v[74:75], v[78:79]
	v_pk_fma_f32 v[78:79], v[82:83], v[82:83], v[80:81]
	v_pk_fma_f32 v[80:81], v[90:91], v[90:91], v[86:87]
	v_mov_b32_e32 v100, v9
	v_mov_b32_e32 v101, v5
	v_pk_fma_f32 v[82:83], v[98:99], v[98:99], v[88:89]
	v_pk_fma_f32 v[74:75], v[76:77], v[76:77], v[74:75]
	v_pk_fma_f32 v[76:77], v[84:85], v[84:85], v[78:79]
	v_pk_fma_f32 v[78:79], v[92:93], v[92:93], v[80:81]
	v_pk_fma_f32 v[80:81], v[100:101], v[100:101], v[82:83]
	v_mov_b32_e32 v82, v78
	v_mov_b32_e32 v83, v74
	v_mov_b32_e32 v74, v79
	v_mov_b32_e32 v78, v80
	v_mov_b32_e32 v79, v76
	v_pk_add_f32 v[74:75], v[82:83], v[74:75]
	v_mov_b32_e32 v76, v81
	v_pk_add_f32 v[74:75], v[74:75], v[78:79]
	s_waitcnt vmcnt(0)
	v_pk_add_f32 v[68:69], v[68:69], 1.0 op_sel_hi:[1,0]
	v_pk_add_f32 v[74:75], v[74:75], v[76:77]
	ds_bpermute_b32 v77, v42, v75
	ds_bpermute_b32 v76, v42, v74
	v_pk_add_f32 v[70:71], v[70:71], 1.0 op_sel_hi:[1,0]
	s_waitcnt lgkmcnt(0)
	v_pk_add_f32 v[74:75], v[74:75], v[76:77]
	ds_bpermute_b32 v77, v43, v75
	ds_bpermute_b32 v76, v43, v74
	s_waitcnt lgkmcnt(0)
	v_pk_add_f32 v[74:75], v[74:75], v[76:77]
	ds_bpermute_b32 v77, v44, v75
	ds_bpermute_b32 v76, v44, v74
	s_waitcnt lgkmcnt(0)
	v_pk_add_f32 v[74:75], v[74:75], v[76:77]
	ds_bpermute_b32 v77, v45, v75
	ds_bpermute_b32 v76, v45, v74
	s_waitcnt lgkmcnt(0)
	v_pk_add_f32 v[74:75], v[74:75], v[76:77]
	ds_bpermute_b32 v77, v46, v75
	ds_bpermute_b32 v76, v46, v74
	s_waitcnt lgkmcnt(0)
	v_pk_add_f32 v[74:75], v[74:75], v[76:77]
	ds_bpermute_b32 v77, v47, v75
	ds_bpermute_b32 v76, v47, v74
	s_waitcnt lgkmcnt(0)
	v_pk_add_f32 v[74:75], v[74:75], v[76:77]
	s_nop 0
	v_pk_fma_f32 v[74:75], v[74:75], s[12:13], v[34:35] op_sel_hi:[1,0,0]
	v_lshl_add_u64 v[76:77], v[72:73], 0, v[28:29]
	v_mul_f32_e32 v31, 0x4b800000, v75
	v_cmp_gt_f32_e32 vcc, s17, v75
	v_add_u32_e32 v35, s28, v35
	s_nop 0
	v_cndmask_b32_e32 v31, v75, v31, vcc
	v_rsq_f32_e32 v31, v31
	s_nop 0
	v_mul_f32_e32 v33, 0x45800000, v31
	v_cndmask_b32_e32 v78, v31, v33, vcc
	v_pk_mul_f32 v[48:49], v[48:49], v[78:79] op_sel_hi:[1,0]
	v_pk_mul_f32 v[50:51], v[50:51], v[78:79] op_sel_hi:[1,0]
	v_pk_fma_f32 v[48:49], v[68:69], v[48:49], v[64:65]
	v_pk_fma_f32 v[50:51], v[70:71], v[50:51], v[66:67]
	v_cvt_pk_bf16_f32 v48, v48, v49
	v_cvt_pk_bf16_f32 v49, v50, v51
	global_store_dwordx2 v[24:25], v[48:49], off
	v_cmp_gt_f32_e32 vcc, s17, v74
	v_pk_mul_f32 v[52:53], v[52:53], v[78:79] op_sel_hi:[1,0]
	v_pk_mul_f32 v[54:55], v[54:55], v[78:79] op_sel_hi:[1,0]
	v_pk_mul_f32 v[56:57], v[56:57], v[78:79] op_sel_hi:[1,0]
	v_pk_mul_f32 v[58:59], v[58:59], v[78:79] op_sel_hi:[1,0]
	v_pk_mul_f32 v[60:61], v[60:61], v[78:79] op_sel_hi:[1,0]
	v_pk_mul_f32 v[62:63], v[62:63], v[78:79] op_sel_hi:[1,0]
	v_pk_add_f32 v[156:157], v[156:157], 1.0 op_sel_hi:[1,0]
	v_pk_add_f32 v[158:159], v[158:159], 1.0 op_sel_hi:[1,0]
	v_pk_fma_f32 v[52:53], v[52:53], v[156:157], v[144:145]
	v_pk_fma_f32 v[54:55], v[54:55], v[158:159], v[146:147]
	v_cvt_pk_bf16_f32 v52, v52, v53
	v_cvt_pk_bf16_f32 v53, v54, v55
	global_store_dwordx2 v[24:25], v[52:53], off offset:512
	v_pk_add_f32 v[160:161], v[160:161], 1.0 op_sel_hi:[1,0]
	v_pk_add_f32 v[162:163], v[162:163], 1.0 op_sel_hi:[1,0]
	v_pk_fma_f32 v[56:57], v[56:57], v[160:161], v[148:149]
	v_pk_fma_f32 v[58:59], v[58:59], v[162:163], v[150:151]
	v_cvt_pk_bf16_f32 v56, v56, v57
	v_cvt_pk_bf16_f32 v57, v58, v59
	global_store_dwordx2 v[24:25], v[56:57], off offset:1024
	v_pk_add_f32 v[164:165], v[164:165], 1.0 op_sel_hi:[1,0]
	v_pk_add_f32 v[166:167], v[166:167], 1.0 op_sel_hi:[1,0]
	v_pk_fma_f32 v[60:61], v[60:61], v[164:165], v[152:153]
	v_pk_fma_f32 v[62:63], v[62:63], v[166:167], v[154:155]
	v_cvt_pk_bf16_f32 v60, v60, v61
	v_cvt_pk_bf16_f32 v61, v62, v63
	global_store_dwordx2 v[24:25], v[60:61], off offset:1536
	v_mul_f32_e32 v27, 0x4b800000, v74
	v_cndmask_b32_e32 v27, v74, v27, vcc
	v_rsq_f32_e32 v27, v27
	v_lshl_add_u64 v[54:55], v[20:21], 0, v[36:37]
	v_lshl_add_u64 v[24:25], v[24:25], 0, s[6:7]
	v_mul_f32_e32 v29, 0x45800000, v27
	v_cndmask_b32_e32 v56, v27, v29, vcc
	v_pk_mul_f32 v[14:15], v[14:15], v[56:57] op_sel_hi:[1,0]
	v_pk_mul_f32 v[16:17], v[16:17], v[56:57] op_sel_hi:[1,0]
	v_pk_mul_f32 v[10:11], v[10:11], v[56:57] op_sel_hi:[1,0]
	v_pk_mul_f32 v[12:13], v[12:13], v[56:57] op_sel_hi:[1,0]
	v_pk_mul_f32 v[6:7], v[6:7], v[56:57] op_sel_hi:[1,0]
	v_pk_mul_f32 v[8:9], v[8:9], v[56:57] op_sel_hi:[1,0]
	v_pk_mul_f32 v[2:3], v[2:3], v[56:57] op_sel_hi:[1,0]
	v_pk_mul_f32 v[4:5], v[4:5], v[56:57] op_sel_hi:[1,0]
	v_cmp_lt_i32_e32 vcc, s18, v35
	s_or_b64 s[8:9], vcc, s[8:9]
	v_pk_add_f32 v[188:189], v[188:189], 1.0 op_sel_hi:[1,0]
	v_pk_add_f32 v[190:191], v[190:191], 1.0 op_sel_hi:[1,0]
	v_pk_fma_f32 v[14:15], v[14:15], v[188:189], v[172:173]
	v_pk_fma_f32 v[16:17], v[16:17], v[190:191], v[174:175]
	v_cvt_pk_bf16_f32 v14, v14, v15
	v_cvt_pk_bf16_f32 v15, v16, v17
	global_store_dwordx2 v[54:55], v[14:15], off
	v_pk_add_f32 v[192:193], v[192:193], 1.0 op_sel_hi:[1,0]
	v_pk_add_f32 v[194:195], v[194:195], 1.0 op_sel_hi:[1,0]
	v_pk_fma_f32 v[10:11], v[10:11], v[192:193], v[176:177]
	v_pk_fma_f32 v[12:13], v[12:13], v[194:195], v[178:179]
	v_cvt_pk_bf16_f32 v10, v10, v11
	v_cvt_pk_bf16_f32 v11, v12, v13
	global_store_dwordx2 v[54:55], v[10:11], off offset:512
	v_pk_add_f32 v[196:197], v[196:197], 1.0 op_sel_hi:[1,0]
	v_pk_add_f32 v[198:199], v[198:199], 1.0 op_sel_hi:[1,0]
	v_pk_fma_f32 v[6:7], v[6:7], v[196:197], v[180:181]
	v_pk_fma_f32 v[8:9], v[8:9], v[198:199], v[182:183]
	v_cvt_pk_bf16_f32 v6, v6, v7
	v_cvt_pk_bf16_f32 v7, v8, v9
	global_store_dwordx2 v[54:55], v[6:7], off offset:1024
	v_pk_add_f32 v[200:201], v[200:201], 1.0 op_sel_hi:[1,0]
	v_pk_add_f32 v[202:203], v[202:203], 1.0 op_sel_hi:[1,0]
	v_pk_fma_f32 v[2:3], v[2:3], v[200:201], v[184:185]
	v_pk_fma_f32 v[4:5], v[4:5], v[202:203], v[186:187]
	v_cvt_pk_bf16_f32 v2, v2, v3
	v_cvt_pk_bf16_f32 v3, v4, v5
	global_store_dwordx2 v[54:55], v[2:3], off offset:1536
	s_andn2_b64 exec, exec, s[8:9]
	s_cbranch_execz .LBB0_174
